# speedup vs baseline: 1.0023x; 1.0023x over previous
; #define PG8_STAGE(bufoff, gbase, voff) do { _Pragma("unroll") for (int _i = 0; _i < 2; ++_i) \
;         __builtin_amdgcn_global_load_lds((const unsigned*)((const char*)(gbase) + (voff)[_i]), (PG8_LAS unsigned*)(lds + (bufoff) + ldsw + _i * 8192), 16, 0, 0); } while (0)
; #define PG8_LDA(dst, b, h) do { _Pragma("unroll") for (int m = 0; m < 4; ++m) _Pragma("unroll") for (int k = 0; k < 2; ++k) dst[m][k] = *(const PG8_LAS bf16x8*)(lds + PG8_SA(b, h) + aoff + m * 2048 + k * 1024); } while (0)
; #define PG8_LDB(dst, b, h) do { _Pragma("unroll") for (int n = 0; n < 2; ++n) _Pragma("unroll") for (int k = 0; k < 2; ++k) dst[n][k] = *(const PG8_LAS bf16x8*)(lds + PG8_SB(b, h) + boff + n * 2048 + k * 1024); } while (0)
; #define PG8_MMA(ai, bj, At, Bt) do { __builtin_amdgcn_s_setprio(1); _Pragma("unroll") for (int m = 0; m < 4; ++m) _Pragma("unroll") for (int n = 0; n < 2; ++n) _Pragma("unroll") for (int k = 0; k < 2; ++k) \
;         acc[ai][bj][m][n] = __builtin_amdgcn_mfma_f32_16x16x32_bf16(Bt[n][k], At[m][k], acc[ai][bj][m][n], 0, 0, 0); __builtin_amdgcn_s_setprio(0); } while (0)
; template <class Epi, class Sched, bool ALIGN_EPI = false, bool SP2 = false>
; __device__ __forceinline__ void gemm_phase(PG8_LAS unsigned char* lds, const Gemm g, const Sched& S, const Epi& E, const int tid) {
;     ...
;         const bool has_next = S.next(ui + 1, nxt);
;         const char* nA = has_next ? (const char*)g.A + (size_t)nxt.pm * tstep : cA; const char* nB = has_next ? (const char*)g.Bt + (size_t)nxt.pn * tstep : cB;
;         for (int t = 0; t < nt; t += 2) {
;             const bool last = (t == nt - 2);
;             const char* a1 = cA + (size_t)(t + 1) * kstep;
;             const char* a2 = last ? nA : cA + (size_t)(t + 2) * kstep; const char* b2 = last ? nB : cB + (size_t)(t + 2) * kstep;
;             const char* a3 = a2 + kstep; const char* b3 = b2 + kstep;
;             if (last && has_next) S.a_ready(nxt);
;             if constexpr (SP2) {
;             PG8_LDB(B0, 0, 0); PG8_LDB(B1, 0, 1); PG8_SCHED; PG8_LDA(At, 0, 0); PG8_STAGE(PG8_SA(1, 1), a1 + hstep, voffA);
;             PG8_WAIT_V(8); PG8_WAIT_L(0); PG8_BAR; PG8_MMA(0, 0, At, B0); PG8_MMA(0, 1, At, B1); PG8_BAR; PG8_SCHED;
;             PG8_LDA(At, 0, 1); PG8_STAGE(PG8_SB(0, 0), b2, voffB); PG8_STAGE(PG8_SB(0, 1), b2 + hstep, voffB); PG8_STAGE(PG8_SA(0, 0), a2, voffA);
.LBB0_59:
	s_add_u32 s26, s26, 0x80
	s_addc_u32 s27, s27, 0
	s_add_u32 s36, s30, 0x100
	s_addc_u32 s37, s31, 0
	s_mov_b32 s30, 0
	s_add_i32 s44, s30, 2
	s_add_u32 s45, s26, 0x80
	s_addc_u32 s31, s27, 0
	s_add_i32 s63, 0, 0x10000
	s_cmp_eq_u32 s58, s30
	s_cselect_b32 s31, s21, s31
	s_cselect_b32 s30, s20, s45
	s_cselect_b32 s65, s23, s37
	s_cselect_b32 s64, s22, s36
	s_add_i32 s45, 0, 0x14000
	v_add_u32_e32 v154, s63, v143
	v_add_u32_e32 v158, s45, v143
	ds_read_b128 v[138:141], v154
	ds_read_b128 v[146:149], v154 offset:1024
	ds_read_b128 v[150:153], v154 offset:2048
	ds_read_b128 v[154:157], v154 offset:3072
	ds_read_b128 v[162:165], v158
	ds_read_b128 v[166:169], v158 offset:1024
	ds_read_b128 v[170:173], v158 offset:2048
	ds_read_b128 v[184:187], v158 offset:3072
	v_lshl_add_u64 v[158:159], s[26:27], 0, v[134:135]
	s_add_i32 m0, s47, 0xc000
	ds_read_b128 v[188:191], v145
	ds_read_b128 v[192:195], v145 offset:1024
	ds_read_b128 v[208:211], v145 offset:2048
	ds_read_b128 v[214:217], v145 offset:3072
	ds_read_b128 v[218:221], v145 offset:4096
	ds_read_b128 v[222:225], v145 offset:5120
	ds_read_b128 v[226:229], v145 offset:6144
	ds_read_b128 v[230:233], v145 offset:7168
	global_load_lds_dwordx4 v[158:159], off
	v_lshl_add_u64 v[158:159], s[26:27], 0, v[136:137]
	s_add_i32 m0, s47, 0xe000
	s_nop 0
	global_load_lds_dwordx4 v[158:159], off
	s_waitcnt vmcnt(32)
	s_waitcnt lgkmcnt(0)
	s_barrier
	s_setprio 1
	s_waitcnt lgkmcnt(0)
	v_mfma_f32_16x16x32_bf16 v[124:127], v[138:141], v[188:191], 0
	v_mfma_f32_16x16x32_bf16 v[120:123], v[150:153], v[188:191], 0
	v_mfma_f32_16x16x32_bf16 v[108:111], v[138:141], v[208:211], 0
	v_mfma_f32_16x16x32_bf16 v[104:107], v[150:153], v[208:211], 0
	v_mfma_f32_16x16x32_bf16 v[92:95], v[138:141], v[218:221], 0
	v_mfma_f32_16x16x32_bf16 v[88:91], v[150:153], v[218:221], 0
	v_mfma_f32_16x16x32_bf16 v[76:79], v[138:141], v[226:229], 0
	v_mfma_f32_16x16x32_bf16 v[72:75], v[150:153], v[226:229], 0
	v_mfma_f32_16x16x32_bf16 v[124:127], v[146:149], v[192:195], v[124:127]
	v_mfma_f32_16x16x32_bf16 v[120:123], v[154:157], v[192:195], v[120:123]
	v_mfma_f32_16x16x32_bf16 v[108:111], v[146:149], v[214:217], v[108:111]
	v_mfma_f32_16x16x32_bf16 v[104:107], v[154:157], v[214:217], v[104:107]
	v_mfma_f32_16x16x32_bf16 v[92:95], v[146:149], v[222:225], v[92:95]
	v_mfma_f32_16x16x32_bf16 v[88:91], v[154:157], v[222:225], v[88:91]
	v_mfma_f32_16x16x32_bf16 v[76:79], v[146:149], v[230:233], v[76:79]
	v_mfma_f32_16x16x32_bf16 v[72:75], v[154:157], v[230:233], v[72:75]
	s_setprio 0
	s_setprio 1
	v_mfma_f32_16x16x32_bf16 v[116:119], v[162:165], v[188:191], 0
	v_mfma_f32_16x16x32_bf16 v[112:115], v[170:173], v[188:191], 0
	v_mfma_f32_16x16x32_bf16 v[100:103], v[162:165], v[208:211], 0
	v_mfma_f32_16x16x32_bf16 v[96:99], v[170:173], v[208:211], 0
	v_mfma_f32_16x16x32_bf16 v[84:87], v[162:165], v[218:221], 0
	v_mfma_f32_16x16x32_bf16 v[80:83], v[170:173], v[218:221], 0
	v_mfma_f32_16x16x32_bf16 v[68:71], v[162:165], v[226:229], 0
	v_mfma_f32_16x16x32_bf16 v[64:67], v[170:173], v[226:229], 0
	v_mfma_f32_16x16x32_bf16 v[116:119], v[166:169], v[192:195], v[116:119]
	v_mfma_f32_16x16x32_bf16 v[112:115], v[184:187], v[192:195], v[112:115]
	v_mfma_f32_16x16x32_bf16 v[100:103], v[166:169], v[214:217], v[100:103]
	v_mfma_f32_16x16x32_bf16 v[96:99], v[184:187], v[214:217], v[96:99]
	v_mfma_f32_16x16x32_bf16 v[84:87], v[166:169], v[222:225], v[84:87]
	v_mfma_f32_16x16x32_bf16 v[80:83], v[184:187], v[222:225], v[80:83]
	v_mfma_f32_16x16x32_bf16 v[68:71], v[166:169], v[230:233], v[68:71]
	v_mfma_f32_16x16x32_bf16 v[64:67], v[184:187], v[230:233], v[64:67]
	s_setprio 0
	s_barrier
	s_add_i32 s63, s63, s46
	v_lshl_add_u64 v[158:159], s[64:65], 0, v[160:161]
	s_mov_b32 m0, s63
	ds_read_b128 v[188:191], v145 offset:16384
	ds_read_b128 v[192:195], v145 offset:17408
	ds_read_b128 v[208:211], v145 offset:18432
	ds_read_b128 v[214:217], v145 offset:19456
	ds_read_b128 v[218:221], v145 offset:20480
	ds_read_b128 v[222:225], v145 offset:21504
	ds_read_b128 v[226:229], v145 offset:22528
	ds_read_b128 v[230:233], v145 offset:23552
	global_load_lds_dwordx4 v[158:159], off
	s_add_i32 m0, s63, 0x2000
	v_lshl_add_u64 v[174:175], s[64:65], 0, v[132:133]
	s_add_u32 s64, s64, s12
	s_addc_u32 s65, s65, 0
	s_add_i32 s45, s45, s46
	global_load_lds_dwordx4 v[174:175], off
	v_lshl_add_u64 v[178:179], s[64:65], 0, v[160:161]
	s_mov_b32 m0, s45
	v_lshl_add_u64 v[180:181], s[64:65], 0, v[132:133]
	global_load_lds_dwordx4 v[178:179], off
	s_add_i32 m0, s45, 0x2000
	v_lshl_add_u64 v[196:197], s[30:31], 0, v[128:129]
	global_load_lds_dwordx4 v[180:181], off
	s_mov_b32 m0, s47
	v_lshl_add_u64 v[198:199], s[30:31], 0, v[130:131]
	global_load_lds_dwordx4 v[196:197], off
	s_mov_b32 m0, s48
	s_nop 0
	global_load_lds_dwordx4 v[198:199], off
	s_cmp_lt_u32 s59, 2
	s_cbranch_scc1 .Lmy_w8_0
	s_waitcnt vmcnt(32)
	s_branch .Lmy_wj_0
